# prep conv items: the two look-back rows are loaded with the item's 24 prefetched loads (one exposed latency per item instead of two)
# baseline (speedup 1.0000x reference)
; __device__ __forceinline__ float bf_lo(unsigned u) { return __uint_as_float(u << 16); }
; __device__ __forceinline__ float bf_hi(unsigned u) { return __uint_as_float(u & 0xffff0000u); }
; __device__ __forceinline__ void prep_items(const Ctx& C, int l, int w0, int nw) {
;     ...
;             if (s0 > 0) {
; #pragma unroll
;     ...
;                     const bf16_t* row = P + (size_t)(tok0 - back) * PP + lane * 8;
;                     const u32x4 u = *(const u32x4*)row, cc = *(const u32x4*)(row + 1024);
;                     float t[8] = {bf_lo(u.x) * bf_lo(cc.x), bf_hi(u.x) * bf_hi(cc.x), bf_lo(u.y) * bf_lo(cc.y), bf_hi(u.y) * bf_hi(cc.y), bf_lo(u.z) * bf_lo(cc.z), bf_hi(u.z) * bf_hi(cc.z), bf_lo(u.w) * bf_lo(cc.w), bf_hi(u.w) * bf_hi(cc.w)};
; #pragma unroll
;                     for (int e = 0; e < 8; ++e) { if (back == 2) c2[e] = t[e]; else c1[e] = t[e]; }
;                 }
;             }
.LBB0_473:
	v_mad_i64_i32 v[30:31], s[10:11], s1, v233, v[26:27]
	s_waitcnt vmcnt(0)
	v_mov_b32_e32 v32, v208
	v_mov_b32_e32 v33, v209
	v_mov_b32_e32 v34, v210
	v_mov_b32_e32 v35, v211
	v_mov_b32_e32 v36, v216
	v_mov_b32_e32 v37, v217
	v_mov_b32_e32 v38, v218
	v_mov_b32_e32 v39, v219
	s_add_i32 s6, s1, 1
	s_waitcnt vmcnt(1)
	v_and_b32_e32 v30, 0xffff0000, v32
	v_lshlrev_b32_e32 v31, 16, v32
	s_waitcnt vmcnt(0)
	v_and_b32_e32 v40, 0xffff0000, v36
	v_lshlrev_b32_e32 v41, 16, v36
	v_and_b32_e32 v32, 0xffff0000, v33
	v_lshlrev_b32_e32 v33, 16, v33
	v_and_b32_e32 v36, 0xffff0000, v37
	v_lshlrev_b32_e32 v37, 16, v37
	v_pk_mul_f32 v[30:31], v[30:31], v[40:41]
	v_pk_mul_f32 v[40:41], v[32:33], v[36:37]
	v_and_b32_e32 v32, 0xffff0000, v34
	v_lshlrev_b32_e32 v33, 16, v34
	v_and_b32_e32 v36, 0xffff0000, v38
	v_lshlrev_b32_e32 v37, 16, v38
	v_pk_mul_f32 v[44:45], v[32:33], v[36:37]
	v_and_b32_e32 v32, 0xffff0000, v35
	v_lshlrev_b32_e32 v33, 16, v35
	v_and_b32_e32 v34, 0xffff0000, v39
	v_lshlrev_b32_e32 v35, 16, v39
	v_mad_i64_i32 v[36:37], s[10:11], s6, v233, v[26:27]
	v_pk_mul_f32 v[46:47], v[32:33], v[34:35]
	v_mov_b32_e32 v32, v220
	v_mov_b32_e32 v33, v221
	v_mov_b32_e32 v34, v222
	v_mov_b32_e32 v35, v223
	s_nop 0
	v_mov_b32_e32 v36, v224
	v_mov_b32_e32 v37, v225
	v_mov_b32_e32 v38, v226
	v_mov_b32_e32 v39, v227
	s_waitcnt vmcnt(1)
	v_and_b32_e32 v48, 0xffff0000, v32
	v_lshlrev_b32_e32 v49, 16, v32
	s_waitcnt vmcnt(0)
	v_and_b32_e32 v50, 0xffff0000, v36
	v_lshlrev_b32_e32 v51, 16, v36
	v_and_b32_e32 v32, 0xffff0000, v33
	v_lshlrev_b32_e32 v33, 16, v33
	v_and_b32_e32 v36, 0xffff0000, v37
	v_lshlrev_b32_e32 v37, 16, v37
	v_pk_mul_f32 v[48:49], v[48:49], v[50:51]
	v_pk_mul_f32 v[32:33], v[32:33], v[36:37]
	v_and_b32_e32 v36, 0xffff0000, v34
	v_lshlrev_b32_e32 v37, 16, v34
	v_and_b32_e32 v50, 0xffff0000, v38
	v_lshlrev_b32_e32 v51, 16, v38
	v_pk_mul_f32 v[50:51], v[36:37], v[50:51]
	v_and_b32_e32 v34, 0xffff0000, v35
	v_lshlrev_b32_e32 v35, 16, v35
	v_and_b32_e32 v36, 0xffff0000, v39
	v_lshlrev_b32_e32 v37, 16, v39
	v_pk_mul_f32 v[34:35], v[34:35], v[36:37]
	v_mov_b32_e32 v36, v51
	v_mov_b32_e32 v38, v35
	v_mov_b32_e32 v39, v34
	v_mov_b32_e32 v37, v50
	v_mov_b32_e32 v34, v33
	v_mov_b32_e32 v35, v32
	v_mov_b32_e32 v32, v49
	v_mov_b32_e32 v33, v48
	v_mov_b32_e32 v50, v47
	v_mov_b32_e32 v51, v46
	v_mov_b32_e32 v48, v45
	v_mov_b32_e32 v49, v44
	v_mov_b32_e32 v46, v41
	v_mov_b32_e32 v47, v40
	v_mov_b32_e32 v44, v31
	v_mov_b32_e32 v45, v30

; __device__ __forceinline__ float bf_lo(unsigned u) { return __uint_as_float(u << 16); }
; __device__ __forceinline__ float bf_hi(unsigned u) { return __uint_as_float(u & 0xffff0000u); }
; __device__ __forceinline__ void prep_items(const Ctx& C, int l, int w0, int nw) {
;     ...
;         for (int it = w0; it < T_ / 8; it += nw) {
;             const int tok0 = it * 8, s0 = tok0 & (S_ - 1);
;             float c1[8], c2[8];
; #pragma unroll
;             for (int e = 0; e < 8; ++e) { c1[e] = 0.f; c2[e] = 0.f; }
;             if (s0 > 0) {
; #pragma unroll
;     ...
;                     const bf16_t* row = P + (size_t)(tok0 - back) * PP + lane * 8;
;                     const u32x4 u = *(const u32x4*)row, cc = *(const u32x4*)(row + 1024);
;                     float t[8] = {bf_lo(u.x) * bf_lo(cc.x), bf_hi(u.x) * bf_hi(cc.x), bf_lo(u.y) * bf_lo(cc.y), bf_hi(u.y) * bf_hi(cc.y), bf_lo(u.z) * bf_lo(cc.z), bf_hi(u.z) * bf_hi(cc.z), bf_lo(u.w) * bf_lo(cc.w), bf_hi(u.w) * bf_hi(cc.w)};
; #pragma unroll
;                     for (int e = 0; e < 8; ++e) { if (back == 2) c2[e] = t[e]; else c1[e] = t[e]; }
;                 }
;             }
; #pragma unroll
;             for (int tt = 0; tt < 8; ++tt) {
;                 const bf16_t* row = P + (size_t)(tok0 + tt) * PP + lane * 8;
;                 const u32x4 u = *(const u32x4*)row, bb = *(const u32x4*)(row + 512), cc = *(const u32x4*)(row + 1024);
.LBB0_475:
	s_add_i32 s6, s1, 2
	v_mad_i64_i32 v[212:213], s[10:11], s6, v233, v[26:27]
	global_load_dwordx4 v[98:101], v[212:213], off
	global_load_dwordx4 v[102:105], v[212:213], off offset:1024
	global_load_dwordx4 v[106:109], v[212:213], off offset:2048
	s_add_i32 s6, s1, 3
	v_mad_i64_i32 v[212:213], s[10:11], s6, v233, v[26:27]
	global_load_dwordx4 v[110:113], v[212:213], off
	global_load_dwordx4 v[114:117], v[212:213], off offset:1024
	global_load_dwordx4 v[118:121], v[212:213], off offset:2048
	s_add_i32 s6, s1, 4
	v_mad_i64_i32 v[212:213], s[10:11], s6, v233, v[26:27]
	global_load_dwordx4 v[122:125], v[212:213], off
	global_load_dwordx4 v[126:129], v[212:213], off offset:1024
	global_load_dwordx4 v[130:133], v[212:213], off offset:2048
	s_add_i32 s6, s1, 5
	v_mad_i64_i32 v[212:213], s[10:11], s6, v233, v[26:27]
	global_load_dwordx4 v[134:137], v[212:213], off
	global_load_dwordx4 v[138:141], v[212:213], off offset:1024
	global_load_dwordx4 v[142:145], v[212:213], off offset:2048
	s_add_i32 s6, s1, 6
	v_mad_i64_i32 v[212:213], s[10:11], s6, v233, v[26:27]
	global_load_dwordx4 v[146:149], v[212:213], off
	global_load_dwordx4 v[150:153], v[212:213], off offset:1024
	global_load_dwordx4 v[154:157], v[212:213], off offset:2048
	s_add_i32 s6, s1, 7
	v_mad_i64_i32 v[212:213], s[10:11], s6, v233, v[26:27]
	global_load_dwordx4 v[158:161], v[212:213], off
	global_load_dwordx4 v[162:165], v[212:213], off offset:1024
	global_load_dwordx4 v[166:169], v[212:213], off offset:2048
	s_add_i32 s6, s1, 8
	v_mad_i64_i32 v[212:213], s[10:11], s6, v233, v[26:27]
	global_load_dwordx4 v[170:173], v[212:213], off
	global_load_dwordx4 v[174:177], v[212:213], off offset:1024
	global_load_dwordx4 v[178:181], v[212:213], off offset:2048
	s_add_i32 s6, s1, 9
	v_mad_i64_i32 v[212:213], s[10:11], s6, v233, v[26:27]
	global_load_dwordx4 v[182:185], v[212:213], off
	global_load_dwordx4 v[186:189], v[212:213], off offset:1024
	global_load_dwordx4 v[190:193], v[212:213], off offset:2048
	v_mad_i64_i32 v[212:213], s[10:11], s1, v233, v[26:27]
	global_load_dwordx4 v[208:211], v[212:213], off
	global_load_dwordx4 v[216:219], v[212:213], off offset:2048
	s_add_i32 s6, s1, 1
	v_mad_i64_i32 v[212:213], s[10:11], s6, v233, v[26:27]
	global_load_dwordx4 v[220:223], v[212:213], off
	global_load_dwordx4 v[224:227], v[212:213], off offset:2048
	s_and_b32 s6, s3, 0x7ff
	s_cmp_eq_u32 s6, 0
	s_cbranch_scc0 .LBB0_473
	v_mov_b32_e32 v38, 0
	v_mov_b32_e32 v39, v38
	v_mov_b32_e32 v36, v38
	v_mov_b32_e32 v37, v38
	v_mov_b32_e32 v34, v38
	v_mov_b32_e32 v35, v38
	v_mov_b32_e32 v32, v38
	v_mov_b32_e32 v33, v38
	v_mov_b32_e32 v50, v38
	v_mov_b32_e32 v51, v38
	v_mov_b32_e32 v48, v38
	v_mov_b32_e32 v49, v38
	v_mov_b32_e32 v46, v38
	v_mov_b32_e32 v47, v38
	v_mov_b32_e32 v44, v38
	v_mov_b32_e32 v45, v38
	s_branch .LBB0_474
